# GEMM epilogues in P4 and P6: pairs of 8-byte bf16 row stores merged into 16-byte stores through v_permlane16_swap; P4 queue dequeue atomic issued one epilogue earlier
# baseline (speedup 1.0000x reference)
; #define PG8_WAIT_V(n) asm volatile("s_waitcnt vmcnt(" #n ")" ::: "memory")
; #define PG8_BAR __builtin_amdgcn_s_barrier()
; template <class Epi, class Sched, bool ALIGN_EPI = false, bool SP2 = false>
; __device__ __forceinline__ void gemm_phase(PG8_LAS unsigned char* lds, const Gemm g, const Sched& S, const Epi& E, int tid_in) {
;     ...
;     for (int i = 0; i < 2; ++i) { int R, C; stage_rc(tid * 16 + i * 8192, R, C); const int Rb = Epi::PERM ? ((R & ~31) + perm32(R & 31)) : R;
;         voffA[i] = (unsigned)(R * K + C) * 2u; voffB[i] = (unsigned)(Rb * K + C) * 2u; }
;     const size_t kstep = (size_t)(BK * 2);
;     const size_t hstep = (size_t)HALF * K * 2;
;     const size_t tstep = 2 * hstep;
;     const unsigned ldsw = (unsigned)wid * 1024u;
;     const int aoff = lds_byte(wr * 64 + fr, fq * 8), boff = lds_byte(wc * 32 + fr, fq * 8);
;     ...
;     Unit cur, nxt; int ui = 0;
;     if (!S.next(0, cur)) return;
;     f32x4 acc[2][2][4][2];
; #pragma unroll
;     for (int a = 0; a < 2; ++a)
; #pragma unroll
;         for (int b = 0; b < 2; ++b)
; #pragma unroll
;             for (int m = 0; m < 4; ++m)
; #pragma unroll
;                 for (int n = 0; n < 2; ++n) acc[a][b][m][n] = (f32x4){0.f, 0.f, 0.f, 0.f};
;     bf16x8 At[4][2], B0[2][2], B1[2][2];
;     const char* cA = (const char*)g.A + (size_t)cur.pm * tstep; const char* cB = (const char*)g.Bt + (size_t)cur.pn * tstep;
;     S.a_ready(cur);
;     if constexpr (SP2) {
;         PG8_STAGE(PG8_SB(0, 0), cB, voffB); PG8_STAGE(PG8_SB(0, 1), cB + hstep, voffB); PG8_STAGE(PG8_SA(0, 0), cA, voffA); PG8_STAGE(PG8_SA(0, 1), cA + hstep, voffA);
;         if (wr == 1) PG8_BAR;
;         PG8_WAIT_V(2); PG8_BAR;
;         PG8_STAGE(PG8_SB(1, 0), cB + kstep, voffB); PG8_STAGE(PG8_SA(1, 0), cA + kstep, voffA); PG8_STAGE(PG8_SB(1, 1), cB + hstep + kstep, voffB);
;         PG8_WAIT_V(6); PG8_BAR;
;     } else {
;         PG8_STAGE(PG8_SB(0, 0), cB, voffB); PG8_STAGE(PG8_SA(0, 0), cA, voffA); PG8_STAGE(PG8_SB(0, 1), cB + hstep, voffB); PG8_STAGE(PG8_SA(0, 1), cA + hstep, voffA);
;         if (wr == 1) PG8_BAR;
;         PG8_WAIT_V(4); PG8_BAR;
;         PG8_STAGE(PG8_SB(1, 0), cB + kstep, voffB); PG8_STAGE(PG8_SA(1, 0), cA + kstep, voffA); PG8_STAGE(PG8_SB(1, 1), cB + hstep + kstep, voffB);
;         PG8_WAIT_V(6); PG8_BAR;
.LBB0_519:
	s_lshl_b32 s2, s2, 5
	s_mov_b64 s[8:9], 0x80
	s_and_b32 s2, s2, 0x60
	s_add_i32 m0, s49, 0x18000
	v_lshl_add_u64 v[6:7], v[6:7], 0, s[8:9]
	s_lshl_b32 s16, s1, 13
	s_lshl_b32 s17, s2, 7
	s_waitcnt vmcnt(2)
	s_barrier
	global_load_lds_dwordx4 v[6:7], off
	v_lshl_add_u64 v[4:5], v[4:5], 0, s[8:9]
	s_add_i32 m0, s49, 0x1a000
	s_add_i32 s72, s49, 0x8000
	s_add_i32 s73, s49, 0xa000
	global_load_lds_dwordx4 v[4:5], off
	v_lshl_add_u64 v[0:1], v[0:1], 0, s[8:9]
	s_mov_b32 m0, s72
	s_add_u32 s14, s50, 0x100080
	global_load_lds_dwordx4 v[0:1], off
	v_lshl_add_u64 v[0:1], v[2:3], 0, s[8:9]
	s_mov_b32 m0, s73
	s_addc_u32 s15, s51, 0
	global_load_lds_dwordx4 v[0:1], off
	s_add_i32 m0, s49, 0x1c000
	v_lshl_add_u64 v[0:1], s[14:15], 0, v[128:129]
	global_load_lds_dwordx4 v[0:1], off
	v_lshl_add_u64 v[0:1], s[14:15], 0, v[130:131]
	s_add_i32 m0, s49, 0x1e000
	s_cmpk_lt_u32 s0, 0x100
	global_load_lds_dwordx4 v[0:1], off
	v_bfe_u32 v1, v8, 4, 2
	v_and_b32_e32 v0, 15, v8
	v_lshlrev_b32_e32 v2, 4, v1
	v_lshl_or_b32 v142, s1, 6, v0
	v_lshl_or_b32 v0, v0, 6, v2
	v_lshlrev_b32_e32 v2, 2, v8
	v_and_b32_e32 v2, 32, v2
	v_bitop3_b32 v3, v0, s16, v2 bitop3:0xde
	s_cselect_b64 s[14:15], -1, 0
	s_add_u32 s16, s12, 0x17a00000
	v_bitop3_b32 v143, v0, s17, v2 bitop3:0xde
	s_addc_u32 s17, s13, 0
	s_add_u32 s20, s12, 0x18200000
	v_lshlrev_b32_e32 v0, 16, v12
	s_addc_u32 s21, s13, 0
	v_and_b32_e32 v0, 0xfffe0000, v0
	v_lshl_or_b32 v134, v1, 2, s2
	s_add_u32 s74, s12, 0x21200000
	v_lshl_add_u32 v0, v13, 13, v0
	v_and_b32_e32 v1, 1, v12
	s_addc_u32 s75, s13, 0
	v_lshl_or_b32 v0, v1, 6, v0
	s_add_u32 s76, s12, 0x18a01800
	v_lshl_add_u32 v136, v14, 1, v0
	v_lshlrev_b32_e32 v0, 16, v9
	s_addc_u32 s77, s13, 0
	v_and_b32_e32 v0, 0xfffe0000, v0
	s_waitcnt vmcnt(6)
	s_add_u32 s78, s12, 0xea00000
	v_lshl_add_u32 v0, v10, 13, v0
	v_and_b32_e32 v1, 1, v9
	s_addc_u32 s79, s13, 0
	v_lshl_or_b32 v0, v1, 6, v0
	s_add_i32 s81, 0, 0x10000
	s_add_i32 s82, 0, 0x14000
	v_mov_b32_e32 v137, v133
	v_lshl_add_u32 v138, v11, 1, v0
	v_mov_b32_e32 v139, v133
	s_movk_i32 s80, 0x45f
	v_add_u32_e32 v144, s81, v143
	v_add_u32_e32 v145, s82, v143
	v_add_u32_e32 v146, 0, v3
	s_mov_b32 s83, 0
	s_mov_b32 s84, 0
	s_barrier
	s_branch .LBB0_522

;     __device__ __forceinline__ bool leader() const { int l; asm volatile("v_mbcnt_lo_u32_b32 %0, -1, 0\n\tv_mbcnt_hi_u32_b32 %0, -1, %0" : "=v"(l)); return wave0 == 0 && l == 0; }
;     __device__ __forceinline__ bool next(int i, Unit& u) const {
;         if (i == 0) { if (leader()) { ring[0] = __hip_atomic_fetch_add(ctr, 1u, __ATOMIC_RELAXED, __HIP_MEMORY_SCOPE_AGENT); ring[1] = __hip_atomic_fetch_add(ctr, 1u, __ATOMIC_RELAXED, __HIP_MEMORY_SCOPE_AGENT); }
;                       __syncthreads(); }
;         else if (leader()) ring[(i + 1) & 3] = __hip_atomic_fetch_add(ctr, 1u, __ATOMIC_RELAXED, __HIP_MEMORY_SCOPE_AGENT);
;         const int id = (int)ring[i & 3]; if (id >= count) return false;
;         const int gsz = 8 * nN, gid = id / gsz, r = id % gsz; u.pm = gid * 8 + (r & 7); u.pn = r >> 3; return true; }
.LBB0_522:
	v_mbcnt_lo_u32_b32 v0, -1, 0
	v_mbcnt_hi_u32_b32 v0, -1, v0
	s_nop 0
	v_cmp_eq_u32_e32 vcc, 0, v0
	s_and_b64 s[0:1], s[4:5], vcc
	s_cmp_eq_u32 s84, 1
	s_cselect_b32 s0, 0, s0
	s_cselect_b32 s1, 0, s1
	s_and_saveexec_b64 s[38:39], s[0:1]
	s_cbranch_execz .LBB0_524
	v_mov_b64_e32 v[0:1], s[12:13]
	s_waitcnt vmcnt(0)
	flat_atomic_add v0, v[0:1], v135 offset:512 sc0
	s_and_b32 s0, s83, 3
	s_xor_b32 s0, s0, 2
	s_lshl_b32 s0, s0, 2
	s_add_i32 s0, s0, 0
	s_add_i32 s0, s0, 0x27f40
	v_mov_b32_e32 v1, s0
	s_waitcnt vmcnt(0) lgkmcnt(0)
	ds_write_b32 v1, v0

; #define PG8_STAGE(bufoff, gbase, voff) do { _Pragma("unroll") for (int _i = 0; _i < 2; ++_i) \
;         __builtin_amdgcn_global_load_lds((const unsigned*)((const char*)(gbase) + (voff)[_i]), (PG8_LAS unsigned*)(lds + (bufoff) + ldsw + _i * 8192), 16, 0, 0); } while (0)
; #define PG8_LDA(dst, b, h) do { _Pragma("unroll") for (int m = 0; m < 4; ++m) _Pragma("unroll") for (int k = 0; k < 2; ++k) dst[m][k] = *(const PG8_LAS bf16x8*)(lds + PG8_SA(b, h) + aoff + m * 2048 + k * 1024); } while (0)
; #define PG8_LDB(dst, b, h) do { _Pragma("unroll") for (int n = 0; n < 2; ++n) _Pragma("unroll") for (int k = 0; k < 2; ++k) dst[n][k] = *(const PG8_LAS bf16x8*)(lds + PG8_SB(b, h) + boff + n * 2048 + k * 1024); } while (0)
; #define PG8_MMA(ai, bj, At, Bt) do { __builtin_amdgcn_s_setprio(1); _Pragma("unroll") for (int m = 0; m < 4; ++m) _Pragma("unroll") for (int n = 0; n < 2; ++n) _Pragma("unroll") for (int k = 0; k < 2; ++k) \
;         acc[ai][bj][m][n] = __builtin_amdgcn_mfma_f32_16x16x32_bf16(Bt[n][k], At[m][k], acc[ai][bj][m][n], 0, 0, 0); __builtin_amdgcn_s_setprio(0); } while (0)
; #define PG8_WAIT_V(n) asm volatile("s_waitcnt vmcnt(" #n ")" ::: "memory")
; #define PG8_WAIT_L(n) asm volatile("s_waitcnt lgkmcnt(" #n ")" ::: "memory")
; #define PG8_BAR __builtin_amdgcn_s_barrier()
; #define PG8_SCHED __builtin_amdgcn_sched_barrier(0)
; template <class Epi, class Sched, bool ALIGN_EPI = false, bool SP2 = false>
; __device__ __forceinline__ void gemm_phase(PG8_LAS unsigned char* lds, const Gemm g, const Sched& S, const Epi& E, int tid_in) {
;     ...
;             PG8_LDB(B0, 0, 0); PG8_LDB(B1, 0, 1); PG8_SCHED; PG8_LDA(At, 0, 0); PG8_STAGE(PG8_SA(1, 1), a1 + hstep, voffA);
;             PG8_WAIT_V(8); PG8_WAIT_L(0); PG8_BAR; PG8_MMA(0, 0, At, B0); PG8_MMA(0, 1, At, B1); PG8_BAR; PG8_SCHED;
;             PG8_LDA(At, 0, 1); PG8_STAGE(PG8_SB(0, 0), b2, voffB); PG8_STAGE(PG8_SB(0, 1), b2 + hstep, voffB); PG8_STAGE(PG8_SA(0, 0), a2, voffA);
;             PG8_WAIT_V(8); PG8_WAIT_L(0); PG8_BAR; PG8_MMA(1, 0, At, B0); PG8_MMA(1, 1, At, B1); PG8_BAR; PG8_SCHED;
.LBB0_527:
	ds_read_b128 v[148:151], v144
	ds_read_b128 v[152:155], v144 offset:1024
	ds_read_b128 v[156:159], v144 offset:2048
	ds_read_b128 v[160:163], v144 offset:3072
	ds_read_b128 v[164:167], v145
	ds_read_b128 v[168:171], v145 offset:1024
	ds_read_b128 v[172:175], v145 offset:2048
	ds_read_b128 v[176:179], v145 offset:3072
	s_add_u32 s25, s50, 0xfff00080
	s_addc_u32 s26, s51, -1
	s_cmp_eq_u32 s24, 60
	s_cselect_b32 s55, s0, s26
	s_cselect_b32 s54, s1, s25
	s_cselect_b32 s53, s2, s23
	s_cselect_b32 s52, s18, s19
	v_lshl_add_u64 v[140:141], s[50:51], 0, v[138:139]
	s_add_i32 m0, s49, 0xc000
	ds_read_b128 v[180:183], v146
	ds_read_b128 v[184:187], v146 offset:1024
	ds_read_b128 v[188:191], v146 offset:2048
	ds_read_b128 v[192:195], v146 offset:3072
	ds_read_b128 v[196:199], v146 offset:4096
	ds_read_b128 v[200:203], v146 offset:5120
	ds_read_b128 v[204:207], v146 offset:6144
	ds_read_b128 v[208:211], v146 offset:7168
	global_load_lds_dwordx4 v[140:141], off
	v_lshl_add_u64 v[140:141], s[50:51], 0, v[136:137]
	s_add_i32 m0, s49, 0xe000
	s_nop 0
	global_load_lds_dwordx4 v[140:141], off
	s_waitcnt vmcnt(8)
	s_waitcnt lgkmcnt(0)
	s_barrier
	s_setprio 1
	s_waitcnt lgkmcnt(0)
	v_mfma_f32_16x16x32_bf16 v[124:127], v[148:151], v[180:183], v[124:127]
	v_mfma_f32_16x16x32_bf16 v[120:123], v[156:159], v[180:183], v[120:123]
	v_mfma_f32_16x16x32_bf16 v[112:115], v[148:151], v[188:191], v[112:115]
	v_mfma_f32_16x16x32_bf16 v[104:107], v[156:159], v[188:191], v[104:107]
	v_mfma_f32_16x16x32_bf16 v[96:99], v[148:151], v[196:199], v[96:99]
	v_mfma_f32_16x16x32_bf16 v[88:91], v[156:159], v[196:199], v[88:91]
	v_mfma_f32_16x16x32_bf16 v[80:83], v[148:151], v[204:207], v[80:83]
	v_mfma_f32_16x16x32_bf16 v[72:75], v[156:159], v[204:207], v[72:75]
	v_mfma_f32_16x16x32_bf16 v[124:127], v[152:155], v[184:187], v[124:127]
	v_mfma_f32_16x16x32_bf16 v[120:123], v[160:163], v[184:187], v[120:123]
	v_mfma_f32_16x16x32_bf16 v[112:115], v[152:155], v[192:195], v[112:115]
	v_mfma_f32_16x16x32_bf16 v[104:107], v[160:163], v[192:195], v[104:107]
	v_mfma_f32_16x16x32_bf16 v[96:99], v[152:155], v[200:203], v[96:99]
	v_mfma_f32_16x16x32_bf16 v[88:91], v[160:163], v[200:203], v[88:91]
	v_mfma_f32_16x16x32_bf16 v[80:83], v[152:155], v[208:211], v[80:83]
	v_mfma_f32_16x16x32_bf16 v[72:75], v[160:163], v[208:211], v[72:75]
	s_setprio 0
	s_setprio 1
	v_mfma_f32_16x16x32_bf16 v[116:119], v[164:167], v[180:183], v[116:119]
	v_mfma_f32_16x16x32_bf16 v[108:111], v[172:175], v[180:183], v[108:111]
	v_mfma_f32_16x16x32_bf16 v[100:103], v[164:167], v[188:191], v[100:103]
	v_mfma_f32_16x16x32_bf16 v[92:95], v[172:175], v[188:191], v[92:95]
	v_mfma_f32_16x16x32_bf16 v[84:87], v[164:167], v[196:199], v[84:87]
	v_mfma_f32_16x16x32_bf16 v[76:79], v[172:175], v[196:199], v[76:79]
	v_mfma_f32_16x16x32_bf16 v[68:71], v[164:167], v[204:207], v[68:71]
	v_mfma_f32_16x16x32_bf16 v[64:67], v[172:175], v[204:207], v[64:67]
	v_mfma_f32_16x16x32_bf16 v[116:119], v[168:171], v[184:187], v[116:119]
	v_mfma_f32_16x16x32_bf16 v[108:111], v[176:179], v[184:187], v[108:111]
	v_mfma_f32_16x16x32_bf16 v[100:103], v[168:171], v[192:195], v[100:103]
	v_mfma_f32_16x16x32_bf16 v[92:95], v[176:179], v[192:195], v[92:95]
	v_mfma_f32_16x16x32_bf16 v[84:87], v[168:171], v[200:203], v[84:87]
	v_mfma_f32_16x16x32_bf16 v[76:79], v[176:179], v[200:203], v[76:79]
	v_mfma_f32_16x16x32_bf16 v[68:71], v[168:171], v[208:211], v[68:71]
	v_mfma_f32_16x16x32_bf16 v[64:67], v[176:179], v[208:211], v[64:67]
	s_setprio 0
	s_barrier
	s_add_i32 s25, s81, s64
	v_lshl_add_u64 v[140:141], s[52:53], 0, v[128:129]
	s_mov_b32 m0, s25
	ds_read_b128 v[180:183], v146 offset:16384
	ds_read_b128 v[184:187], v146 offset:17408
	ds_read_b128 v[188:191], v146 offset:18432
	ds_read_b128 v[192:195], v146 offset:19456
	ds_read_b128 v[196:199], v146 offset:20480
	ds_read_b128 v[200:203], v146 offset:21504
	ds_read_b128 v[204:207], v146 offset:22528
	ds_read_b128 v[208:211], v146 offset:23552
	global_load_lds_dwordx4 v[140:141], off
	s_add_i32 m0, s25, 0x2000
	s_add_u32 s26, s52, 0x100000
	v_lshl_add_u64 v[212:213], s[52:53], 0, v[130:131]
	s_addc_u32 s27, s53, 0
	s_add_i32 s25, s82, s64
	global_load_lds_dwordx4 v[212:213], off
	v_lshl_add_u64 v[214:215], s[26:27], 0, v[128:129]
	s_mov_b32 m0, s25
	v_lshl_add_u64 v[216:217], s[54:55], 0, v[130:131]
	global_load_lds_dwordx4 v[214:215], off
	v_lshl_add_u64 v[214:215], s[26:27], 0, v[130:131]
	s_add_i32 m0, s25, 0x2000
	s_nop 0
	global_load_lds_dwordx4 v[214:215], off
	v_lshl_add_u64 v[214:215], s[54:55], 0, v[128:129]
	s_mov_b32 m0, s49
	s_nop 0
	global_load_lds_dwordx4 v[214:215], off
	s_mov_b32 m0, s67
	s_nop 0
	global_load_lds_dwordx4 v[216:217], off
	s_waitcnt vmcnt(8)
	s_waitcnt lgkmcnt(0)
	s_barrier
; #define PG8_STAGE(bufoff, gbase, voff) do { _Pragma("unroll") for (int _i = 0; _i < 2; ++_i) \
;         __builtin_amdgcn_global_load_lds((const unsigned*)((const char*)(gbase) + (voff)[_i]), (PG8_LAS unsigned*)(lds + (bufoff) + ldsw + _i * 8192), 16, 0, 0); } while (0)
; #define PG8_LDA(dst, b, h) do { _Pragma("unroll") for (int m = 0; m < 4; ++m) _Pragma("unroll") for (int k = 0; k < 2; ++k) dst[m][k] = *(const PG8_LAS bf16x8*)(lds + PG8_SA(b, h) + aoff + m * 2048 + k * 1024); } while (0)
; #define PG8_LDB(dst, b, h) do { _Pragma("unroll") for (int n = 0; n < 2; ++n) _Pragma("unroll") for (int k = 0; k < 2; ++k) dst[n][k] = *(const PG8_LAS bf16x8*)(lds + PG8_SB(b, h) + boff + n * 2048 + k * 1024); } while (0)
; #define PG8_MMA(ai, bj, At, Bt) do { __builtin_amdgcn_s_setprio(1); _Pragma("unroll") for (int m = 0; m < 4; ++m) _Pragma("unroll") for (int n = 0; n < 2; ++n) _Pragma("unroll") for (int k = 0; k < 2; ++k) \
;         acc[ai][bj][m][n] = __builtin_amdgcn_mfma_f32_16x16x32_bf16(Bt[n][k], At[m][k], acc[ai][bj][m][n], 0, 0, 0); __builtin_amdgcn_s_setprio(0); } while (0)
; #define PG8_WAIT_V(n) asm volatile("s_waitcnt vmcnt(" #n ")" ::: "memory")
; #define PG8_WAIT_L(n) asm volatile("s_waitcnt lgkmcnt(" #n ")" ::: "memory")
; #define PG8_BAR __builtin_amdgcn_s_barrier()
; #define PG8_SCHED __builtin_amdgcn_sched_barrier(0)
; template <class Epi, class Sched, bool ALIGN_EPI = false, bool SP2 = false>
; __device__ __forceinline__ void gemm_phase(PG8_LAS unsigned char* lds, const Gemm g, const Sched& S, const Epi& E, int tid_in) {
;     ...
;             PG8_WAIT_V(8); PG8_WAIT_L(0); PG8_BAR; PG8_MMA(1, 0, At, B0); PG8_MMA(1, 1, At, B1); PG8_BAR; PG8_SCHED;
;             PG8_LDB(B0, 1, 0); PG8_LDB(B1, 1, 1); PG8_SCHED; PG8_LDA(At, 1, 0); PG8_STAGE(PG8_SA(0, 1), a2 + hstep, voffA);
;             PG8_WAIT_V(8); PG8_WAIT_L(0); PG8_BAR; PG8_MMA(0, 0, At, B0); PG8_MMA(0, 1, At, B1); PG8_BAR; PG8_SCHED;
;             PG8_LDA(At, 1, 1); PG8_STAGE(PG8_SB(1, 0), b3, voffB); PG8_STAGE(PG8_SB(1, 1), b3 + hstep, voffB); PG8_STAGE(PG8_SA(1, 0), a3, voffA);
;             PG8_WAIT_V(8); PG8_WAIT_L(0); PG8_BAR; PG8_MMA(1, 0, At, B0); PG8_MMA(1, 1, At, B1); PG8_BAR; PG8_SCHED;
	s_setprio 1
	s_waitcnt lgkmcnt(0)
	v_mfma_f32_16x16x32_bf16 v[60:63], v[148:151], v[180:183], v[60:63]
	v_mfma_f32_16x16x32_bf16 v[56:59], v[156:159], v[180:183], v[56:59]
	v_mfma_f32_16x16x32_bf16 v[48:51], v[148:151], v[188:191], v[48:51]
	v_mfma_f32_16x16x32_bf16 v[40:43], v[156:159], v[188:191], v[40:43]
	v_mfma_f32_16x16x32_bf16 v[32:35], v[148:151], v[196:199], v[32:35]
	v_mfma_f32_16x16x32_bf16 v[24:27], v[156:159], v[196:199], v[24:27]
	v_mfma_f32_16x16x32_bf16 v[16:19], v[148:151], v[204:207], v[16:19]
	v_mfma_f32_16x16x32_bf16 v[8:11], v[156:159], v[204:207], v[8:11]
	v_mfma_f32_16x16x32_bf16 v[60:63], v[152:155], v[184:187], v[60:63]
	v_mfma_f32_16x16x32_bf16 v[56:59], v[160:163], v[184:187], v[56:59]
	v_mfma_f32_16x16x32_bf16 v[48:51], v[152:155], v[192:195], v[48:51]
	v_mfma_f32_16x16x32_bf16 v[40:43], v[160:163], v[192:195], v[40:43]
	v_mfma_f32_16x16x32_bf16 v[32:35], v[152:155], v[200:203], v[32:35]
	v_mfma_f32_16x16x32_bf16 v[24:27], v[160:163], v[200:203], v[24:27]
	v_mfma_f32_16x16x32_bf16 v[16:19], v[152:155], v[208:211], v[16:19]
	v_mfma_f32_16x16x32_bf16 v[8:11], v[160:163], v[208:211], v[8:11]
	s_setprio 0
	s_setprio 1
	v_mfma_f32_16x16x32_bf16 v[52:55], v[164:167], v[180:183], v[52:55]
	v_mfma_f32_16x16x32_bf16 v[44:47], v[172:175], v[180:183], v[44:47]
	v_mfma_f32_16x16x32_bf16 v[36:39], v[164:167], v[188:191], v[36:39]
	v_mfma_f32_16x16x32_bf16 v[28:31], v[172:175], v[188:191], v[28:31]
	v_mfma_f32_16x16x32_bf16 v[20:23], v[164:167], v[196:199], v[20:23]
	v_mfma_f32_16x16x32_bf16 v[12:15], v[172:175], v[196:199], v[12:15]
	v_mfma_f32_16x16x32_bf16 v[4:7], v[164:167], v[204:207], v[4:7]
	v_mfma_f32_16x16x32_bf16 v[0:3], v[172:175], v[204:207], v[0:3]
	v_mfma_f32_16x16x32_bf16 v[52:55], v[168:171], v[184:187], v[52:55]
	v_mfma_f32_16x16x32_bf16 v[44:47], v[176:179], v[184:187], v[44:47]
	v_mfma_f32_16x16x32_bf16 v[36:39], v[168:171], v[192:195], v[36:39]
	v_mfma_f32_16x16x32_bf16 v[28:31], v[176:179], v[192:195], v[28:31]
	v_mfma_f32_16x16x32_bf16 v[20:23], v[168:171], v[200:203], v[20:23]
	v_mfma_f32_16x16x32_bf16 v[12:15], v[176:179], v[200:203], v[12:15]
	v_mfma_f32_16x16x32_bf16 v[4:7], v[168:171], v[208:211], v[4:7]
	v_mfma_f32_16x16x32_bf16 v[0:3], v[176:179], v[208:211], v[0:3]
	s_setprio 0
	s_barrier
	s_add_i32 s25, 0, 0x18000
	v_add_u32_e32 v132, s25, v143
	s_add_i32 s28, 0, 0x1c000
	ds_read_b128 v[148:151], v132
	ds_read_b128 v[152:155], v132 offset:1024
	ds_read_b128 v[156:159], v132 offset:2048
	ds_read_b128 v[160:163], v132 offset:3072
	v_add_u32_e32 v132, s28, v143
	ds_read_b128 v[164:167], v132
	ds_read_b128 v[168:171], v132 offset:1024
	ds_read_b128 v[172:175], v132 offset:2048
	ds_read_b128 v[176:179], v132 offset:3072
	s_add_u32 s26, s54, 0x100000
	s_addc_u32 s27, s55, 0
	s_mov_b32 m0, s70
	v_lshl_add_u64 v[218:219], s[26:27], 0, v[128:129]
	ds_read_b128 v[180:183], v146 offset:32768
	ds_read_b128 v[184:187], v146 offset:33792
	ds_read_b128 v[188:191], v146 offset:34816
	ds_read_b128 v[192:195], v146 offset:35840
	ds_read_b128 v[196:199], v146 offset:36864
	ds_read_b128 v[200:203], v146 offset:37888
	ds_read_b128 v[204:207], v146 offset:38912
	ds_read_b128 v[208:211], v146 offset:39936
	global_load_lds_dwordx4 v[218:219], off
	v_lshl_add_u64 v[218:219], s[26:27], 0, v[130:131]
	s_mov_b32 m0, s71
	s_nop 0
	global_load_lds_dwordx4 v[218:219], off
	s_waitcnt vmcnt(8)
	s_waitcnt lgkmcnt(0)
	s_barrier
	s_setprio 1
	s_waitcnt lgkmcnt(0)
	v_mfma_f32_16x16x32_bf16 v[124:127], v[148:151], v[180:183], v[124:127]
	v_mfma_f32_16x16x32_bf16 v[120:123], v[156:159], v[180:183], v[120:123]
	v_mfma_f32_16x16x32_bf16 v[112:115], v[148:151], v[188:191], v[112:115]
	v_mfma_f32_16x16x32_bf16 v[104:107], v[156:159], v[188:191], v[104:107]
	v_mfma_f32_16x16x32_bf16 v[96:99], v[148:151], v[196:199], v[96:99]
	v_mfma_f32_16x16x32_bf16 v[88:91], v[156:159], v[196:199], v[88:91]
	v_mfma_f32_16x16x32_bf16 v[80:83], v[148:151], v[204:207], v[80:83]
	v_mfma_f32_16x16x32_bf16 v[72:75], v[156:159], v[204:207], v[72:75]
	v_mfma_f32_16x16x32_bf16 v[124:127], v[152:155], v[184:187], v[124:127]
	v_mfma_f32_16x16x32_bf16 v[120:123], v[160:163], v[184:187], v[120:123]
	v_mfma_f32_16x16x32_bf16 v[112:115], v[152:155], v[192:195], v[112:115]
	v_mfma_f32_16x16x32_bf16 v[104:107], v[160:163], v[192:195], v[104:107]
	v_mfma_f32_16x16x32_bf16 v[96:99], v[152:155], v[200:203], v[96:99]
	v_mfma_f32_16x16x32_bf16 v[88:91], v[160:163], v[200:203], v[88:91]
	v_mfma_f32_16x16x32_bf16 v[80:83], v[152:155], v[208:211], v[80:83]
	v_mfma_f32_16x16x32_bf16 v[72:75], v[160:163], v[208:211], v[72:75]
	s_setprio 0
	s_setprio 1
	v_mfma_f32_16x16x32_bf16 v[116:119], v[164:167], v[180:183], v[116:119]
	v_mfma_f32_16x16x32_bf16 v[108:111], v[172:175], v[180:183], v[108:111]
	v_mfma_f32_16x16x32_bf16 v[100:103], v[164:167], v[188:191], v[100:103]
	v_mfma_f32_16x16x32_bf16 v[92:95], v[172:175], v[188:191], v[92:95]
	v_mfma_f32_16x16x32_bf16 v[84:87], v[164:167], v[196:199], v[84:87]
	v_mfma_f32_16x16x32_bf16 v[76:79], v[172:175], v[196:199], v[76:79]
	v_mfma_f32_16x16x32_bf16 v[68:71], v[164:167], v[204:207], v[68:71]
	v_mfma_f32_16x16x32_bf16 v[64:67], v[172:175], v[204:207], v[64:67]
	v_mfma_f32_16x16x32_bf16 v[116:119], v[168:171], v[184:187], v[116:119]
	v_mfma_f32_16x16x32_bf16 v[108:111], v[176:179], v[184:187], v[108:111]
	v_mfma_f32_16x16x32_bf16 v[100:103], v[168:171], v[192:195], v[100:103]
	v_mfma_f32_16x16x32_bf16 v[92:95], v[176:179], v[192:195], v[92:95]
	v_mfma_f32_16x16x32_bf16 v[84:87], v[168:171], v[200:203], v[84:87]
	v_mfma_f32_16x16x32_bf16 v[76:79], v[176:179], v[200:203], v[76:79]
	v_mfma_f32_16x16x32_bf16 v[68:71], v[168:171], v[208:211], v[68:71]
	v_mfma_f32_16x16x32_bf16 v[64:67], v[176:179], v[208:211], v[64:67]
	s_setprio 0
	s_barrier
; #define PG8_WAIT_V(n) asm volatile("s_waitcnt vmcnt(" #n ")" ::: "memory")
; #define PG8_BAR __builtin_amdgcn_s_barrier()
;     __device__ __forceinline__ bool next(int i, Unit& u) const {
;         if (i == 0) { if (leader()) { ring[0] = __hip_atomic_fetch_add(ctr, 1u, __ATOMIC_RELAXED, __HIP_MEMORY_SCOPE_AGENT); ring[1] = __hip_atomic_fetch_add(ctr, 1u, __ATOMIC_RELAXED, __HIP_MEMORY_SCOPE_AGENT); }
;                       __syncthreads(); }
; template <class Epi, class Sched, bool ALIGN_EPI = false, bool SP2 = false>
; __device__ __forceinline__ void gemm_phase(PG8_LAS unsigned char* lds, const Gemm g, const Sched& S, const Epi& E, int tid_in) {
;     ...
;             PG8_LDA(At, 1, 1); PG8_STAGE(PG8_SB(1, 0), b3, voffB); PG8_STAGE(PG8_SB(1, 1), b3 + hstep, voffB); PG8_STAGE(PG8_SA(1, 0), a3, voffA);
;             PG8_WAIT_V(8); PG8_WAIT_L(0); PG8_BAR; PG8_MMA(1, 0, At, B0); PG8_MMA(1, 1, At, B1); PG8_BAR; PG8_SCHED;
;             } else {
;             PG8_LDB(B0, 0, 0); PG8_SCHED; PG8_LDA(At, 0, 0); PG8_STAGE(PG8_SA(1, 1), a1 + hstep, voffA);
;             PG8_WAIT_L(8); PG8_BAR; PG8_WAIT_L(0); PG8_MMA(0, 0, At, B0); PG8_BAR; PG8_SCHED;
;             PG8_LDB(B1, 0, 1); PG8_STAGE(PG8_SB(0, 0), b2, voffB);
;             PG8_BAR; PG8_WAIT_L(0); PG8_MMA(0, 1, At, B1); PG8_BAR;
;             PG8_LDA(At, 0, 1); PG8_STAGE(PG8_SA(0, 0), a2, voffA);
;             PG8_BAR; PG8_WAIT_L(0); PG8_MMA(1, 0, At, B0); PG8_BAR; PG8_SCHED;
;             PG8_STAGE(PG8_SB(0, 1), b2 + hstep, voffB);
;             PG8_WAIT_V(6); PG8_BAR; PG8_MMA(1, 1, At, B1); PG8_BAR;
;             PG8_LDB(B0, 1, 0); PG8_SCHED; PG8_LDA(At, 1, 0); PG8_STAGE(PG8_SA(0, 1), a2 + hstep, voffA);
;             PG8_WAIT_L(8); PG8_BAR; PG8_WAIT_L(0); PG8_MMA(0, 0, At, B0); PG8_BAR; PG8_SCHED;
;             PG8_LDB(B1, 1, 1); PG8_STAGE(PG8_SB(1, 0), b3, voffB);
;             PG8_BAR; PG8_WAIT_L(0); PG8_MMA(0, 1, At, B1); PG8_BAR;
;             PG8_LDA(At, 1, 1); PG8_STAGE(PG8_SA(1, 0), a3, voffA);
;             PG8_BAR; PG8_WAIT_L(0); PG8_MMA(1, 0, At, B0); PG8_BAR; PG8_SCHED;
;             PG8_STAGE(PG8_SB(1, 1), b3 + hstep, voffB);
;             PG8_WAIT_V(6); PG8_BAR; PG8_MMA(1, 1, At, B1); PG8_BAR;
;             }
;         }
;         if constexpr (ALIGN_EPI) { if (wr == 0) PG8_BAR; }
;         if constexpr (!Epi::AFTER_DRAIN) { E(acc, cur, wr, wc, fr, fq); S.done(cur); }
;         if (!has_next) break;
	s_add_i32 s25, s25, s64
	v_lshl_add_u64 v[140:141], v[140:141], 0, s[8:9]
	s_mov_b32 m0, s25
	ds_read_b128 v[180:183], v146 offset:49152
	ds_read_b128 v[184:187], v146 offset:50176
	ds_read_b128 v[188:191], v146 offset:51200
	ds_read_b128 v[192:195], v146 offset:52224
	ds_read_b128 v[196:199], v146 offset:53248
	ds_read_b128 v[200:203], v146 offset:54272
	ds_read_b128 v[204:207], v146 offset:55296
	ds_read_b128 v[208:211], v146 offset:56320
	global_load_lds_dwordx4 v[140:141], off
	s_add_i32 m0, s25, 0x2000
	s_add_u32 s26, s52, 0x100080
	v_lshl_add_u64 v[140:141], v[212:213], 0, s[8:9]
	s_addc_u32 s27, s53, 0
	s_add_i32 s25, s28, s64
	global_load_lds_dwordx4 v[140:141], off
	v_lshl_add_u64 v[140:141], s[26:27], 0, v[128:129]
	s_mov_b32 m0, s25
	s_nop 0
	global_load_lds_dwordx4 v[140:141], off
	v_lshl_add_u64 v[140:141], s[26:27], 0, v[130:131]
	s_add_i32 m0, s25, 0x2000
	s_nop 0
	global_load_lds_dwordx4 v[140:141], off
	v_lshl_add_u64 v[140:141], v[214:215], 0, s[8:9]
	s_mov_b32 m0, s72
	s_nop 0
	global_load_lds_dwordx4 v[140:141], off
	v_lshl_add_u64 v[140:141], v[216:217], 0, s[8:9]
	s_mov_b32 m0, s73
	s_nop 0
	global_load_lds_dwordx4 v[140:141], off
	s_waitcnt vmcnt(8)
	s_waitcnt lgkmcnt(0)
	s_barrier
	s_setprio 1
	s_waitcnt lgkmcnt(0)
	v_mfma_f32_16x16x32_bf16 v[60:63], v[148:151], v[180:183], v[60:63]
	v_mfma_f32_16x16x32_bf16 v[56:59], v[156:159], v[180:183], v[56:59]
	v_mfma_f32_16x16x32_bf16 v[48:51], v[148:151], v[188:191], v[48:51]
	v_mfma_f32_16x16x32_bf16 v[40:43], v[156:159], v[188:191], v[40:43]
	v_mfma_f32_16x16x32_bf16 v[32:35], v[148:151], v[196:199], v[32:35]
	v_mfma_f32_16x16x32_bf16 v[24:27], v[156:159], v[196:199], v[24:27]
	v_mfma_f32_16x16x32_bf16 v[16:19], v[148:151], v[204:207], v[16:19]
	v_mfma_f32_16x16x32_bf16 v[8:11], v[156:159], v[204:207], v[8:11]
	v_mfma_f32_16x16x32_bf16 v[60:63], v[152:155], v[184:187], v[60:63]
	v_mfma_f32_16x16x32_bf16 v[56:59], v[160:163], v[184:187], v[56:59]
	v_mfma_f32_16x16x32_bf16 v[48:51], v[152:155], v[192:195], v[48:51]
	v_mfma_f32_16x16x32_bf16 v[40:43], v[160:163], v[192:195], v[40:43]
	v_mfma_f32_16x16x32_bf16 v[32:35], v[152:155], v[200:203], v[32:35]
	v_mfma_f32_16x16x32_bf16 v[24:27], v[160:163], v[200:203], v[24:27]
	v_mfma_f32_16x16x32_bf16 v[16:19], v[152:155], v[208:211], v[16:19]
	v_mfma_f32_16x16x32_bf16 v[8:11], v[160:163], v[208:211], v[8:11]
	s_setprio 0
	s_setprio 1
	v_mfma_f32_16x16x32_bf16 v[52:55], v[164:167], v[180:183], v[52:55]
	v_mfma_f32_16x16x32_bf16 v[44:47], v[172:175], v[180:183], v[44:47]
	v_mfma_f32_16x16x32_bf16 v[36:39], v[164:167], v[188:191], v[36:39]
	v_mfma_f32_16x16x32_bf16 v[28:31], v[172:175], v[188:191], v[28:31]
	v_mfma_f32_16x16x32_bf16 v[20:23], v[164:167], v[196:199], v[20:23]
	v_mfma_f32_16x16x32_bf16 v[12:15], v[172:175], v[196:199], v[12:15]
	v_mfma_f32_16x16x32_bf16 v[4:7], v[164:167], v[204:207], v[4:7]
	v_mfma_f32_16x16x32_bf16 v[0:3], v[172:175], v[204:207], v[0:3]
	v_mfma_f32_16x16x32_bf16 v[52:55], v[168:171], v[184:187], v[52:55]
	v_mfma_f32_16x16x32_bf16 v[44:47], v[176:179], v[184:187], v[44:47]
	v_mfma_f32_16x16x32_bf16 v[36:39], v[168:171], v[192:195], v[36:39]
	v_mfma_f32_16x16x32_bf16 v[28:31], v[176:179], v[192:195], v[28:31]
	v_mfma_f32_16x16x32_bf16 v[20:23], v[168:171], v[200:203], v[20:23]
	v_mfma_f32_16x16x32_bf16 v[12:15], v[176:179], v[200:203], v[12:15]
	v_mfma_f32_16x16x32_bf16 v[4:7], v[168:171], v[208:211], v[4:7]
	v_mfma_f32_16x16x32_bf16 v[0:3], v[176:179], v[208:211], v[0:3]
	s_setprio 0
	s_barrier
	s_cmp_eq_u32 s24, 8
	s_cbranch_scc0 .Lqf_mid_skip
	s_cmp_eq_u32 s84, 1
	s_cbranch_scc0 .Lqf_mid_skip
	s_and_b64 s[86:87], s[4:5], 1
	s_cbranch_scc0 .Lqf_mid_skip
	s_mov_b64 s[86:87], exec
	s_mov_b64 exec, 1
	s_add_i32 s85, s83, 1
	s_and_b32 s85, s85, 3
	s_lshl_b32 s85, s85, 2
	s_add_i32 s85, s85, 0x27f40
	v_mov_b32_e32 v224, s85
	ds_write_b32 v224, v220
	s_mov_b64 exec, s[86:87]
.Lqf_mid_skip:
	s_add_i32 s24, s24, 2
	s_add_u32 s19, s19, 0x100
	s_addc_u32 s23, s23, 0
	s_add_u32 s50, s50, 0x100
	s_addc_u32 s51, s51, 0
	s_cmp_gt_u32 s24, 61
	s_cbranch_scc0 .LBB0_527
	s_and_b64 vcc, exec, s[14:15]
	s_cbranch_vccz .LBB0_530
	s_barrier
.LBB0_530:
	s_mov_b32 s84, 1
	s_and_b64 s[86:87], s[4:5], 1
	s_cbranch_scc0 .Lqf_epi_skip
	s_mov_b64 s[86:87], exec
	s_mov_b64 exec, 1
	v_mov_b32_e32 v221, 0
	global_atomic_add v220, v221, v135, s[12:13] offset:512 sc0
	s_mov_b64 exec, s[86:87]

; __device__ __forceinline__ unsigned cvt_pk_bf16(float lo, float hi) { unsigned r; asm volatile("v_cvt_pk_bf16_f32 %0, %1, %2" : "=v"(r) : "v"(lo), "v"(hi)); return r; }
;     __device__ __forceinline__ void operator()(const f32x4 (&acc)[2][2][4][2], const Unit& u, int wr, int wc, int fr, int fq) const {
;     ...
;             for (int ai = 0; ai < 2; ++ai)
; #pragma unroll
;                 for (int m = 0; m < 4; ++m) { bf16_t* rowp = hb + (size_t)(row0 + ai * HALF + m * 16) * ldc + col0;
; #pragma unroll
;                     for (int bj = 0; bj < 2; ++bj)
; #pragma unroll
;                         for (int n = 0; n < 2; ++n) { const f32x4 v = acc[ai][bj][m][n] * sc; u32x2 w; w.x = cvt_pk_bf16(v[0], v[1]); w.y = cvt_pk_bf16(v[2], v[3]);
;                             if (ldc == 4096) __builtin_nontemporal_store(w, (u32x2*)(rowp + bj * HALF + n * 16)); else *(u32x2*)(rowp + bj * HALF + n * 16) = w; } }
.LBB0_566:
	v_lshlrev_b32_e32 v132, 1, v134
	v_mad_u64_u32 v[168:169], s[0:1], s50, v166, 0
	v_lshl_add_u64 v[140:141], s[52:53], 0, v[132:133]
	v_mbcnt_lo_u32_b32 v242, -1, 0
	v_mbcnt_hi_u32_b32 v242, -1, v242
	v_and_b32_e32 v240, 16, v242
	v_lshrrev_b32_e32 v242, 1, v240
	v_add_u32_e32 v240, v240, v242
	v_mov_b32_e32 v241, 0
	v_lshl_add_u64 v[140:141], v[140:141], 0, v[240:241]
	v_add3_u32 v169, v169, v160, v167
	v_lshl_add_u64 v[166:167], v[168:169], 1, v[140:141]
	v_pk_mul_f32 v[124:125], v[124:125], s[2:3] op_sel_hi:[1,0]
	v_pk_mul_f32 v[120:121], v[120:121], s[2:3] op_sel_hi:[1,0]
	v_pk_mul_f32 v[116:117], v[116:117], s[2:3] op_sel_hi:[1,0]
	v_pk_mul_f32 v[108:109], v[108:109], s[2:3] op_sel_hi:[1,0]
	v_pk_mul_f32 v[126:127], v[126:127], s[2:3] op_sel_hi:[1,0]
	v_cvt_pk_bf16_f32 v224, v124, v125
	v_pk_mul_f32 v[122:123], v[122:123], s[2:3] op_sel_hi:[1,0]
	v_cvt_pk_bf16_f32 v225, v126, v127
	v_cvt_pk_bf16_f32 v226, v120, v121
	v_cvt_pk_bf16_f32 v227, v122, v123
	s_nop 1
	v_permlane16_swap_b32_e32 v224, v226
	v_permlane16_swap_b32_e32 v225, v227
	flat_store_dwordx4 v[166:167], v[224:227]
	v_pk_mul_f32 v[118:119], v[118:119], s[2:3] op_sel_hi:[1,0]
	v_cvt_pk_bf16_f32 v228, v116, v117
	v_pk_mul_f32 v[110:111], v[110:111], s[2:3] op_sel_hi:[1,0]
	v_cvt_pk_bf16_f32 v229, v118, v119
	v_cvt_pk_bf16_f32 v230, v108, v109
	v_cvt_pk_bf16_f32 v231, v110, v111
	s_nop 1
	v_permlane16_swap_b32_e32 v228, v230
	v_permlane16_swap_b32_e32 v229, v231
	flat_store_dwordx4 v[166:167], v[228:231] offset:256
	v_mad_u64_u32 v[108:109], s[0:1], s50, v164, 0
	v_add3_u32 v109, v109, v160, v165
	v_lshl_add_u64 v[108:109], v[108:109], 1, v[140:141]
	v_pk_mul_f32 v[112:113], v[112:113], s[2:3] op_sel_hi:[1,0]
	v_pk_mul_f32 v[104:105], v[104:105], s[2:3] op_sel_hi:[1,0]
	v_pk_mul_f32 v[100:101], v[100:101], s[2:3] op_sel_hi:[1,0]
	v_pk_mul_f32 v[92:93], v[92:93], s[2:3] op_sel_hi:[1,0]
	v_pk_mul_f32 v[110:111], v[114:115], s[2:3] op_sel_hi:[1,0]
	v_cvt_pk_bf16_f32 v232, v112, v113
	v_pk_mul_f32 v[106:107], v[106:107], s[2:3] op_sel_hi:[1,0]
	v_cvt_pk_bf16_f32 v233, v110, v111
	v_cvt_pk_bf16_f32 v234, v104, v105
	v_cvt_pk_bf16_f32 v235, v106, v107
	s_nop 1
	v_permlane16_swap_b32_e32 v232, v234
	v_permlane16_swap_b32_e32 v233, v235
	flat_store_dwordx4 v[108:109], v[232:235]
	v_pk_mul_f32 v[102:103], v[102:103], s[2:3] op_sel_hi:[1,0]
	v_cvt_pk_bf16_f32 v236, v100, v101
	v_pk_mul_f32 v[94:95], v[94:95], s[2:3] op_sel_hi:[1,0]
	v_cvt_pk_bf16_f32 v237, v102, v103
	v_cvt_pk_bf16_f32 v238, v92, v93
	v_cvt_pk_bf16_f32 v239, v94, v95
	s_nop 1
	v_permlane16_swap_b32_e32 v236, v238
	v_permlane16_swap_b32_e32 v237, v239
	flat_store_dwordx4 v[108:109], v[236:239] offset:256
	v_mad_u64_u32 v[92:93], s[0:1], s50, v162, 0
	v_add3_u32 v93, v93, v160, v163
	v_lshl_add_u64 v[92:93], v[92:93], 1, v[140:141]
	v_pk_mul_f32 v[96:97], v[96:97], s[2:3] op_sel_hi:[1,0]
	v_pk_mul_f32 v[88:89], v[88:89], s[2:3] op_sel_hi:[1,0]
	v_pk_mul_f32 v[84:85], v[84:85], s[2:3] op_sel_hi:[1,0]
	v_pk_mul_f32 v[76:77], v[76:77], s[2:3] op_sel_hi:[1,0]
	v_pk_mul_f32 v[94:95], v[98:99], s[2:3] op_sel_hi:[1,0]
	v_cvt_pk_bf16_f32 v224, v96, v97
	v_pk_mul_f32 v[90:91], v[90:91], s[2:3] op_sel_hi:[1,0]
	v_cvt_pk_bf16_f32 v225, v94, v95
	v_cvt_pk_bf16_f32 v226, v88, v89
	v_cvt_pk_bf16_f32 v227, v90, v91
	s_nop 1
	v_permlane16_swap_b32_e32 v224, v226
	v_permlane16_swap_b32_e32 v225, v227
	flat_store_dwordx4 v[92:93], v[224:227]
	v_pk_mul_f32 v[86:87], v[86:87], s[2:3] op_sel_hi:[1,0]
	v_cvt_pk_bf16_f32 v228, v84, v85
	v_pk_mul_f32 v[78:79], v[78:79], s[2:3] op_sel_hi:[1,0]
	v_cvt_pk_bf16_f32 v229, v86, v87
	v_cvt_pk_bf16_f32 v230, v76, v77
	v_cvt_pk_bf16_f32 v231, v78, v79
	s_nop 1
	v_permlane16_swap_b32_e32 v228, v230
	v_permlane16_swap_b32_e32 v229, v231
	flat_store_dwordx4 v[92:93], v[228:231] offset:256
	v_mad_u64_u32 v[76:77], s[0:1], s50, v159, 0
	v_add3_u32 v77, v77, v160, v161
	v_lshl_add_u64 v[76:77], v[76:77], 1, v[140:141]
	v_pk_mul_f32 v[80:81], v[80:81], s[2:3] op_sel_hi:[1,0]
	v_pk_mul_f32 v[72:73], v[72:73], s[2:3] op_sel_hi:[1,0]
	v_pk_mul_f32 v[68:69], v[68:69], s[2:3] op_sel_hi:[1,0]
	v_pk_mul_f32 v[64:65], v[64:65], s[2:3] op_sel_hi:[1,0]
	v_pk_mul_f32 v[78:79], v[82:83], s[2:3] op_sel_hi:[1,0]
	v_cvt_pk_bf16_f32 v232, v80, v81
	v_pk_mul_f32 v[74:75], v[74:75], s[2:3] op_sel_hi:[1,0]
	v_cvt_pk_bf16_f32 v233, v78, v79
	v_cvt_pk_bf16_f32 v234, v72, v73
	v_cvt_pk_bf16_f32 v235, v74, v75
	s_nop 1
	v_permlane16_swap_b32_e32 v232, v234
	v_permlane16_swap_b32_e32 v233, v235
	flat_store_dwordx4 v[76:77], v[232:235]
	v_pk_mul_f32 v[70:71], v[70:71], s[2:3] op_sel_hi:[1,0]
	v_cvt_pk_bf16_f32 v236, v68, v69
	v_pk_mul_f32 v[66:67], v[66:67], s[2:3] op_sel_hi:[1,0]
	v_cvt_pk_bf16_f32 v237, v70, v71
	v_cvt_pk_bf16_f32 v238, v64, v65
; __device__ __forceinline__ unsigned cvt_pk_bf16(float lo, float hi) { unsigned r; asm volatile("v_cvt_pk_bf16_f32 %0, %1, %2" : "=v"(r) : "v"(lo), "v"(hi)); return r; }
;     __device__ __forceinline__ void operator()(const f32x4 (&acc)[2][2][4][2], const Unit& u, int wr, int wc, int fr, int fq) const {
;     ...
;             for (int ai = 0; ai < 2; ++ai)
; #pragma unroll
;                 for (int m = 0; m < 4; ++m) { bf16_t* rowp = hb + (size_t)(row0 + ai * HALF + m * 16) * ldc + col0;
; #pragma unroll
;                     for (int bj = 0; bj < 2; ++bj)
; #pragma unroll
;                         for (int n = 0; n < 2; ++n) { const f32x4 v = acc[ai][bj][m][n] * sc; u32x2 w; w.x = cvt_pk_bf16(v[0], v[1]); w.y = cvt_pk_bf16(v[2], v[3]);
;                             if (ldc == 4096) __builtin_nontemporal_store(w, (u32x2*)(rowp + bj * HALF + n * 16)); else *(u32x2*)(rowp + bj * HALF + n * 16) = w; } }
	v_cvt_pk_bf16_f32 v239, v66, v67
	s_nop 1
	v_permlane16_swap_b32_e32 v236, v238
	v_permlane16_swap_b32_e32 v237, v239
	flat_store_dwordx4 v[76:77], v[236:239] offset:256
	v_mul_lo_u32 v66, s50, v158
	v_mad_u64_u32 v[64:65], s[0:1], s50, v156, 0
	v_add3_u32 v65, v65, v66, v157
	v_lshl_add_u64 v[64:65], v[64:65], 1, v[140:141]
	v_pk_mul_f32 v[60:61], v[60:61], s[2:3] op_sel_hi:[1,0]
	v_pk_mul_f32 v[56:57], v[56:57], s[2:3] op_sel_hi:[1,0]
	v_pk_mul_f32 v[52:53], v[52:53], s[2:3] op_sel_hi:[1,0]
	v_pk_mul_f32 v[44:45], v[44:45], s[2:3] op_sel_hi:[1,0]
	v_pk_mul_f32 v[62:63], v[62:63], s[2:3] op_sel_hi:[1,0]
	v_cvt_pk_bf16_f32 v224, v60, v61
	v_pk_mul_f32 v[58:59], v[58:59], s[2:3] op_sel_hi:[1,0]
	v_cvt_pk_bf16_f32 v225, v62, v63
	v_cvt_pk_bf16_f32 v226, v56, v57
	v_cvt_pk_bf16_f32 v227, v58, v59
	s_nop 1
	v_permlane16_swap_b32_e32 v224, v226
	v_permlane16_swap_b32_e32 v225, v227
	flat_store_dwordx4 v[64:65], v[224:227]
	v_pk_mul_f32 v[54:55], v[54:55], s[2:3] op_sel_hi:[1,0]
	v_cvt_pk_bf16_f32 v228, v52, v53
	v_pk_mul_f32 v[46:47], v[46:47], s[2:3] op_sel_hi:[1,0]
	v_cvt_pk_bf16_f32 v229, v54, v55
	v_cvt_pk_bf16_f32 v230, v44, v45
	v_cvt_pk_bf16_f32 v231, v46, v47
	s_nop 1
	v_permlane16_swap_b32_e32 v228, v230
	v_permlane16_swap_b32_e32 v229, v231
	flat_store_dwordx4 v[64:65], v[228:231] offset:256
	v_mul_lo_u32 v46, s50, v155
	v_mad_u64_u32 v[44:45], s[0:1], s50, v153, 0
	v_add3_u32 v45, v45, v46, v154
	v_lshl_add_u64 v[44:45], v[44:45], 1, v[140:141]
	v_pk_mul_f32 v[48:49], v[48:49], s[2:3] op_sel_hi:[1,0]
	v_pk_mul_f32 v[40:41], v[40:41], s[2:3] op_sel_hi:[1,0]
	v_pk_mul_f32 v[36:37], v[36:37], s[2:3] op_sel_hi:[1,0]
	v_pk_mul_f32 v[28:29], v[28:29], s[2:3] op_sel_hi:[1,0]
	v_pk_mul_f32 v[46:47], v[50:51], s[2:3] op_sel_hi:[1,0]
	v_cvt_pk_bf16_f32 v232, v48, v49
	v_pk_mul_f32 v[42:43], v[42:43], s[2:3] op_sel_hi:[1,0]
	v_cvt_pk_bf16_f32 v233, v46, v47
	v_cvt_pk_bf16_f32 v234, v40, v41
	v_cvt_pk_bf16_f32 v235, v42, v43
	s_nop 1
	v_permlane16_swap_b32_e32 v232, v234
	v_permlane16_swap_b32_e32 v233, v235
	flat_store_dwordx4 v[44:45], v[232:235]
	v_pk_mul_f32 v[38:39], v[38:39], s[2:3] op_sel_hi:[1,0]
	v_cvt_pk_bf16_f32 v236, v36, v37
	v_pk_mul_f32 v[30:31], v[30:31], s[2:3] op_sel_hi:[1,0]
	v_cvt_pk_bf16_f32 v237, v38, v39
	v_cvt_pk_bf16_f32 v238, v28, v29
	v_cvt_pk_bf16_f32 v239, v30, v31
	s_nop 1
	v_permlane16_swap_b32_e32 v236, v238
	v_permlane16_swap_b32_e32 v237, v239
	flat_store_dwordx4 v[44:45], v[236:239] offset:256
	v_mul_lo_u32 v30, s50, v152
	v_mad_u64_u32 v[28:29], s[0:1], s50, v150, 0
	v_add3_u32 v29, v29, v30, v151
	v_lshl_add_u64 v[28:29], v[28:29], 1, v[140:141]
	v_pk_mul_f32 v[32:33], v[32:33], s[2:3] op_sel_hi:[1,0]
	v_pk_mul_f32 v[24:25], v[24:25], s[2:3] op_sel_hi:[1,0]
	v_pk_mul_f32 v[20:21], v[20:21], s[2:3] op_sel_hi:[1,0]
	v_pk_mul_f32 v[12:13], v[12:13], s[2:3] op_sel_hi:[1,0]
	v_pk_mul_f32 v[30:31], v[34:35], s[2:3] op_sel_hi:[1,0]
	v_cvt_pk_bf16_f32 v224, v32, v33
	v_pk_mul_f32 v[26:27], v[26:27], s[2:3] op_sel_hi:[1,0]
	v_cvt_pk_bf16_f32 v225, v30, v31
	v_cvt_pk_bf16_f32 v226, v24, v25
	v_cvt_pk_bf16_f32 v227, v26, v27
	s_nop 1
	v_permlane16_swap_b32_e32 v224, v226
	v_permlane16_swap_b32_e32 v225, v227
	flat_store_dwordx4 v[28:29], v[224:227]
	v_pk_mul_f32 v[22:23], v[22:23], s[2:3] op_sel_hi:[1,0]
	v_cvt_pk_bf16_f32 v228, v20, v21
	v_pk_mul_f32 v[14:15], v[14:15], s[2:3] op_sel_hi:[1,0]
	v_cvt_pk_bf16_f32 v229, v22, v23
	v_cvt_pk_bf16_f32 v230, v12, v13
	v_cvt_pk_bf16_f32 v231, v14, v15
	s_nop 1
	v_permlane16_swap_b32_e32 v228, v230
	v_permlane16_swap_b32_e32 v229, v231
	flat_store_dwordx4 v[28:29], v[228:231] offset:256
	v_mul_lo_u32 v14, s50, v149
	v_mad_u64_u32 v[12:13], s[0:1], s50, v147, 0
	v_add3_u32 v13, v13, v14, v148
	v_lshl_add_u64 v[12:13], v[12:13], 1, v[140:141]
	v_pk_mul_f32 v[16:17], v[16:17], s[2:3] op_sel_hi:[1,0]
	v_pk_mul_f32 v[8:9], v[8:9], s[2:3] op_sel_hi:[1,0]
	v_pk_mul_f32 v[4:5], v[4:5], s[2:3] op_sel_hi:[1,0]
	v_pk_mul_f32 v[0:1], v[0:1], s[2:3] op_sel_hi:[1,0]
	v_pk_mul_f32 v[14:15], v[18:19], s[2:3] op_sel_hi:[1,0]
	v_cvt_pk_bf16_f32 v232, v16, v17
	v_pk_mul_f32 v[10:11], v[10:11], s[2:3] op_sel_hi:[1,0]
	v_cvt_pk_bf16_f32 v233, v14, v15
	v_cvt_pk_bf16_f32 v234, v8, v9
	v_cvt_pk_bf16_f32 v235, v10, v11
	s_nop 1
	v_permlane16_swap_b32_e32 v232, v234
	v_permlane16_swap_b32_e32 v233, v235
	flat_store_dwordx4 v[12:13], v[232:235]
	v_pk_mul_f32 v[6:7], v[6:7], s[2:3] op_sel_hi:[1,0]
	v_cvt_pk_bf16_f32 v236, v4, v5
	v_pk_mul_f32 v[2:3], v[2:3], s[2:3] op_sel_hi:[1,0]
	v_cvt_pk_bf16_f32 v237, v6, v7
	v_cvt_pk_bf16_f32 v238, v0, v1
	v_cvt_pk_bf16_f32 v239, v2, v3
	s_nop 1
	v_permlane16_swap_b32_e32 v236, v238
	v_permlane16_swap_b32_e32 v237, v239
	flat_store_dwordx4 v[12:13], v[236:239] offset:256

; __device__ __forceinline__ unsigned cvt_pk_bf16(float lo, float hi) { unsigned r; asm volatile("v_cvt_pk_bf16_f32 %0, %1, %2" : "=v"(r) : "v"(lo), "v"(hi)); return r; }
;     __device__ __forceinline__ void operator()(const f32x4 (&acc)[2][2][4][2], const Unit& u, int wr, int wc, int fr, int fq) const {
;         const int row0 = u.pm * BM + wr * 64 + fr, col0 = u.pn * BM + wc * 32 + 4 * fq;
; #pragma unroll
;         for (int ai = 0; ai < 2; ++ai)
; #pragma unroll
;             for (int m = 0; m < 4; ++m) { bf16_t* rowp = O + (size_t)(row0 + ai * HALF + m * 16) * ldc + col0;
; #pragma unroll
;                 for (int bj = 0; bj < 2; ++bj)
; #pragma unroll
;                     for (int n = 0; n < 2; ++n) { const f32x4 v = acc[ai][bj][m][n]; u32x2 w; w.x = cvt_pk_bf16(v[0], v[1]); w.y = cvt_pk_bf16(v[2], v[3]); *(u32x2*)(rowp + bj * HALF + n * 16) = w; } }
;     }
.LBB0_896:
	v_lshl_add_u32 v148, s44, 8, v142
	v_lshl_or_b32 v140, s0, 8, v144
	v_ashrrev_i32_e32 v149, 31, v148
	v_ashrrev_i32_e32 v141, 31, v140
	v_lshlrev_b64 v[150:151], 13, v[148:149]
	v_lshl_add_u64 v[150:151], s[10:11], 0, v[150:151]
	v_lshlrev_b64 v[152:153], 1, v[140:141]
	v_mbcnt_lo_u32_b32 v242, -1, 0
	v_mbcnt_hi_u32_b32 v242, -1, v242
	v_and_b32_e32 v240, 16, v242
	v_lshrrev_b32_e32 v242, 1, v240
	v_add_u32_e32 v240, v240, v242
	v_mov_b32_e32 v241, 0
	v_lshl_add_u64 v[152:153], v[152:153], 0, v[240:241]
	v_lshl_add_u64 v[140:141], v[150:151], 0, v[152:153]
	v_cvt_pk_bf16_f32 v224, v124, v125
	v_cvt_pk_bf16_f32 v225, v126, v127
	v_cvt_pk_bf16_f32 v226, v120, v121
	v_cvt_pk_bf16_f32 v227, v122, v123
	s_nop 1
	v_permlane16_swap_b32_e32 v224, v226
	v_permlane16_swap_b32_e32 v225, v227
	flat_store_dwordx4 v[140:141], v[224:227]
	v_cvt_pk_bf16_f32 v228, v116, v117
	v_cvt_pk_bf16_f32 v229, v118, v119
	v_cvt_pk_bf16_f32 v230, v108, v109
	v_cvt_pk_bf16_f32 v231, v110, v111
	s_nop 1
	v_permlane16_swap_b32_e32 v228, v230
	v_permlane16_swap_b32_e32 v229, v231
	flat_store_dwordx4 v[140:141], v[228:231] offset:256
	v_or_b32_e32 v108, 16, v148
	v_ashrrev_i32_e32 v109, 31, v108
	v_lshlrev_b64 v[108:109], 13, v[108:109]
	v_lshl_add_u64 v[108:109], s[10:11], 0, v[108:109]
	v_lshl_add_u64 v[108:109], v[108:109], 0, v[152:153]
	v_cvt_pk_bf16_f32 v232, v112, v113
	v_cvt_pk_bf16_f32 v233, v114, v115
	v_cvt_pk_bf16_f32 v234, v104, v105
	v_cvt_pk_bf16_f32 v235, v106, v107
	s_nop 1
	v_permlane16_swap_b32_e32 v232, v234
	v_permlane16_swap_b32_e32 v233, v235
	flat_store_dwordx4 v[108:109], v[232:235]
	v_cvt_pk_bf16_f32 v236, v100, v101
	v_cvt_pk_bf16_f32 v237, v102, v103
	v_cvt_pk_bf16_f32 v238, v92, v93
	v_cvt_pk_bf16_f32 v239, v94, v95
	s_nop 1
	v_permlane16_swap_b32_e32 v236, v238
	v_permlane16_swap_b32_e32 v237, v239
	flat_store_dwordx4 v[108:109], v[236:239] offset:256
	v_or_b32_e32 v92, 32, v148
	v_ashrrev_i32_e32 v93, 31, v92
	v_lshlrev_b64 v[92:93], 13, v[92:93]
	v_lshl_add_u64 v[92:93], s[10:11], 0, v[92:93]
	v_lshl_add_u64 v[92:93], v[92:93], 0, v[152:153]
	v_cvt_pk_bf16_f32 v224, v96, v97
	v_cvt_pk_bf16_f32 v225, v98, v99
	v_cvt_pk_bf16_f32 v226, v88, v89
	v_cvt_pk_bf16_f32 v227, v90, v91
	s_nop 1
	v_permlane16_swap_b32_e32 v224, v226
	v_permlane16_swap_b32_e32 v225, v227
	flat_store_dwordx4 v[92:93], v[224:227]
	v_cvt_pk_bf16_f32 v228, v84, v85
	v_cvt_pk_bf16_f32 v229, v86, v87
	v_cvt_pk_bf16_f32 v230, v76, v77
	v_cvt_pk_bf16_f32 v231, v78, v79
	s_nop 1
	v_permlane16_swap_b32_e32 v228, v230
	v_permlane16_swap_b32_e32 v229, v231
	flat_store_dwordx4 v[92:93], v[228:231] offset:256
	v_or_b32_e32 v76, 48, v148
	v_ashrrev_i32_e32 v77, 31, v76
	v_lshlrev_b64 v[76:77], 13, v[76:77]
	v_lshl_add_u64 v[76:77], s[10:11], 0, v[76:77]
	v_lshl_add_u64 v[76:77], v[76:77], 0, v[152:153]
	v_cvt_pk_bf16_f32 v232, v80, v81
	v_cvt_pk_bf16_f32 v233, v82, v83
	v_cvt_pk_bf16_f32 v234, v72, v73
	v_cvt_pk_bf16_f32 v235, v74, v75
	s_nop 1
	v_permlane16_swap_b32_e32 v232, v234
	v_permlane16_swap_b32_e32 v233, v235
	flat_store_dwordx4 v[76:77], v[232:235]
	v_cvt_pk_bf16_f32 v236, v68, v69
	v_cvt_pk_bf16_f32 v237, v70, v71
	v_cvt_pk_bf16_f32 v238, v64, v65
	v_cvt_pk_bf16_f32 v239, v66, v67
	s_nop 1
	v_permlane16_swap_b32_e32 v236, v238
	v_permlane16_swap_b32_e32 v237, v239
	flat_store_dwordx4 v[76:77], v[236:239] offset:256
	v_cvt_pk_bf16_f32 v224, v60, v61
	v_cvt_pk_bf16_f32 v225, v62, v63
	v_add_co_u32_e32 v62, vcc, s26, v140
	v_lshl_add_u64 v[64:65], v[140:141], 0, s[6:7]
	s_nop 0
	v_addc_co_u32_e32 v63, vcc, 0, v141, vcc
	v_cvt_pk_bf16_f32 v226, v56, v57
	v_cvt_pk_bf16_f32 v227, v58, v59
	s_nop 1
	v_permlane16_swap_b32_e32 v224, v226
	v_permlane16_swap_b32_e32 v225, v227
	flat_store_dwordx4 v[64:65], v[224:227]
	v_cvt_pk_bf16_f32 v228, v48, v49
	v_cvt_pk_bf16_f32 v229, v50, v51
	v_cvt_pk_bf16_f32 v230, v40, v41
	v_cvt_pk_bf16_f32 v231, v42, v43
	v_add_co_u32_e32 v48, vcc, s27, v140
	s_nop 1
	v_permlane16_swap_b32_e32 v228, v230
	v_permlane16_swap_b32_e32 v229, v231
	flat_store_dwordx4 v[64:65], v[228:231] offset:256
	v_lshl_add_u64 v[40:41], v[140:141], 0, s[16:17]
	v_cvt_pk_bf16_f32 v232, v52, v53
	v_cvt_pk_bf16_f32 v233, v54, v55
	v_addc_co_u32_e32 v49, vcc, 0, v141, vcc
	v_cvt_pk_bf16_f32 v234, v44, v45
	v_cvt_pk_bf16_f32 v235, v46, v47
	s_nop 1
	v_permlane16_swap_b32_e32 v232, v234
	v_permlane16_swap_b32_e32 v233, v235
	flat_store_dwordx4 v[40:41], v[232:235]
	v_cvt_pk_bf16_f32 v236, v32, v33
	v_cvt_pk_bf16_f32 v237, v34, v35
	v_cvt_pk_bf16_f32 v238, v24, v25
	v_cvt_pk_bf16_f32 v239, v26, v27
	v_add_co_u32_e32 v32, vcc, s66, v140
	s_nop 1
	v_permlane16_swap_b32_e32 v236, v238
	v_permlane16_swap_b32_e32 v237, v239
	flat_store_dwordx4 v[40:41], v[236:239] offset:256
	v_lshl_add_u64 v[24:25], v[140:141], 0, s[20:21]
	v_cvt_pk_bf16_f32 v224, v36, v37
	v_cvt_pk_bf16_f32 v225, v38, v39
	v_addc_co_u32_e32 v33, vcc, 0, v141, vcc
	v_cvt_pk_bf16_f32 v226, v28, v29
	v_cvt_pk_bf16_f32 v227, v30, v31
	s_nop 1
	v_permlane16_swap_b32_e32 v224, v226
	v_permlane16_swap_b32_e32 v225, v227
	flat_store_dwordx4 v[24:25], v[224:227]
	v_cvt_pk_bf16_f32 v228, v16, v17
	v_cvt_pk_bf16_f32 v229, v18, v19
	v_add_co_u32_e32 v16, vcc, s67, v140
	v_cvt_pk_bf16_f32 v230, v8, v9
	v_cvt_pk_bf16_f32 v231, v10, v11
	s_nop 1
	v_permlane16_swap_b32_e32 v228, v230
	v_permlane16_swap_b32_e32 v229, v231
	flat_store_dwordx4 v[24:25], v[228:231] offset:256
	s_nop 0
	v_addc_co_u32_e32 v17, vcc, 0, v141, vcc
	v_lshl_add_u64 v[8:9], v[140:141], 0, s[22:23]
	v_cvt_pk_bf16_f32 v232, v20, v21
	v_cvt_pk_bf16_f32 v233, v22, v23
	s_andn2_b64 vcc, exec, s[2:3]
	s_mov_b64 s[2:3], -1
	v_cvt_pk_bf16_f32 v234, v12, v13
	v_cvt_pk_bf16_f32 v235, v14, v15
	s_nop 1
	v_permlane16_swap_b32_e32 v232, v234
	v_permlane16_swap_b32_e32 v233, v235
	flat_store_dwordx4 v[8:9], v[232:235]
	v_cvt_pk_bf16_f32 v236, v4, v5
	v_cvt_pk_bf16_f32 v237, v6, v7
	v_cvt_pk_bf16_f32 v238, v0, v1
	v_cvt_pk_bf16_f32 v239, v2, v3
	s_nop 1
	v_permlane16_swap_b32_e32 v236, v238
	v_permlane16_swap_b32_e32 v237, v239
	flat_store_dwordx4 v[8:9], v[236:239] offset:256
	s_cbranch_vccnz .LBB0_885
	s_andn2_b64 vcc, exec, s[8:9]
	s_cbranch_vccnz .LBB0_884
	s_barrier
	s_branch .LBB0_884
